# v43 + MLA P.V phases: full lgkmcnt(0) drains replaced by counted waits (in-order LDS queue model), 48 waits
# speedup vs baseline: 1.0066x; 1.0066x over previous
.LBB0_542:
	v_cndmask_b32_e64 v202, v50, v1, s[2:3]
	v_mul_f32_e32 v50, 0xbdd53b94, v202
	v_fmamk_f32 v35, v35, 0x3dd53b94, v50
	v_fmamk_f32 v34, v34, 0x3dd53b94, v50
	v_fmamk_f32 v36, v36, 0x3dd53b94, v50
	v_exp_f32_e32 v231, v35
	v_lshlrev_b32_e32 v35, 4, v161
	v_exp_f32_e32 v229, v34
	v_exp_f32_e32 v227, v36
	v_lshlrev_b32_e32 v34, 3, v161
	v_and_b32_e32 v35, 0xc0, v35
	v_lshlrev_b32_e32 v36, 1, v161
	v_and_or_b32 v35, v34, 24, v35
	v_and_b32_e32 v36, 32, v36
	v_and_b32_e32 v34, 0x100, v34
	s_cmp_lg_u32 0, -1
	v_fmamk_f32 v37, v37, 0x3dd53b94, v50
	v_fmamk_f32 v38, v38, 0x3dd53b94, v50
	v_fmamk_f32 v39, v39, 0x3dd53b94, v50
	v_fmamk_f32 v40, v40, 0x3dd53b94, v50
	v_fmamk_f32 v41, v41, 0x3dd53b94, v50
	v_fmamk_f32 v42, v42, 0x3dd53b94, v50
	v_fmamk_f32 v43, v43, 0x3dd53b94, v50
	v_fmamk_f32 v44, v44, 0x3dd53b94, v50
	v_fmamk_f32 v45, v45, 0x3dd53b94, v50
	v_fmamk_f32 v46, v46, 0x3dd53b94, v50
	v_fmamk_f32 v47, v47, 0x3dd53b94, v50
	v_fmamk_f32 v48, v48, 0x3dd53b94, v50
	v_fmamk_f32 v49, v49, 0x3dd53b94, v50
	v_or3_b32 v34, v35, v36, v34
	s_cselect_b32 s1, 0, 0
	v_exp_f32_e32 v230, v37
	v_exp_f32_e32 v226, v38
	v_exp_f32_e32 v228, v39
	v_exp_f32_e32 v224, v40
	v_exp_f32_e32 v225, v41
	v_exp_f32_e32 v221, v42
	v_exp_f32_e32 v223, v43
	v_exp_f32_e32 v220, v44
	v_exp_f32_e32 v222, v45
	v_exp_f32_e32 v217, v46
	v_exp_f32_e32 v219, v47
	v_exp_f32_e32 v216, v48
	v_exp_f32_e32 v218, v49
	v_add_u32_e32 v200, s1, v34
	s_and_b32 s1, s84, 7
	s_lshl_b32 s1, s1, 9
	s_waitcnt vmcnt(0)
	v_pk_fma_f32 v[146:147], v[32:33], s[34:35], v[50:51] op_sel_hi:[1,0,0]
	v_pk_fma_f32 v[148:149], v[30:31], s[34:35], v[50:51] op_sel_hi:[1,0,0]
	v_pk_fma_f32 v[150:151], v[28:29], s[34:35], v[50:51] op_sel_hi:[1,0,0]
	v_pk_fma_f32 v[152:153], v[26:27], s[34:35], v[50:51] op_sel_hi:[1,0,0]
	v_pk_fma_f32 v[154:155], v[24:25], s[34:35], v[50:51] op_sel_hi:[1,0,0]
	v_pk_fma_f32 v[156:157], v[22:23], s[34:35], v[50:51] op_sel_hi:[1,0,0]
	v_pk_fma_f32 v[162:163], v[20:21], s[34:35], v[50:51] op_sel_hi:[1,0,0]
	v_pk_fma_f32 v[164:165], v[18:19], s[34:35], v[50:51] op_sel_hi:[1,0,0]
	v_lshl_add_u32 v170, v168, 2, v51
	v_lshl_add_u32 v158, v52, 2, v51
	s_add_u32 s20, s4, s1
	v_mov_b64_e32 v[64:65], v[16:17]
	v_mov_b64_e32 v[48:49], v[16:17]
	v_mov_b64_e32 v[32:33], v[16:17]
	s_mov_b32 s17, 1
	s_mov_b32 s0, 0
	v_cmp_gt_u32_e64 s[2:3], 32, v161
	s_mov_b32 s19, 2
	s_addc_u32 s21, s5, 0
	v_mov_b32_e32 v171, 0
	v_mov_b64_e32 v[62:63], v[14:15]
	v_mov_b64_e32 v[60:61], v[12:13]
	v_mov_b64_e32 v[58:59], v[10:11]
	v_mov_b64_e32 v[56:57], v[8:9]
	v_mov_b64_e32 v[54:55], v[6:7]
	v_mov_b64_e32 v[52:53], v[4:5]
	v_mov_b64_e32 v[50:51], v[2:3]
	v_mov_b64_e32 v[46:47], v[14:15]
	v_mov_b64_e32 v[44:45], v[12:13]
	v_mov_b64_e32 v[42:43], v[10:11]
	v_mov_b64_e32 v[40:41], v[8:9]
	v_mov_b64_e32 v[38:39], v[6:7]
	v_mov_b64_e32 v[36:37], v[4:5]
	v_mov_b64_e32 v[34:35], v[2:3]
	v_mov_b64_e32 v[30:31], v[14:15]
	v_mov_b64_e32 v[28:29], v[12:13]
	v_mov_b64_e32 v[26:27], v[10:11]
	v_mov_b64_e32 v[24:25], v[8:9]
	v_mov_b64_e32 v[22:23], v[6:7]
	v_mov_b64_e32 v[20:21], v[4:5]
	v_mov_b64_e32 v[18:19], v[2:3]
	s_mov_b32 s22, 2
	s_waitcnt vmcnt(0)
	s_barrier
	v_mov_b32_e32 v245, v172
	v_ashrrev_i32_e32 v250, 4, v245
	v_xor_b32_e32 v246, v250, v245
	v_lshlrev_b32_e32 v246, 3, v246
	v_lshrrev_b32_e32 v247, 1, v245
	v_and_b32_e32 v246, 0x78, v246
	v_and_b32_e32 v255, 8, v247
	v_lshrrev_b32_e32 v247, 1, v250
	v_bfe_u32 v254, v245, 2, 2
	v_and_b32_e32 v248, 4, v247
	v_lshl_or_b32 v246, v250, 11, v246
	v_and_or_b32 v250, v250, s75, v255
	v_lshlrev_b32_e32 v247, 3, v245
	v_or3_b32 v250, v250, v248, v254
	v_and_b32_e32 v251, 0x60, v245
	v_and_b32_e32 v249, 24, v247
	v_lshlrev_b32_e32 v250, 11, v250
	v_or3_b32 v250, v250, v251, v249
	v_ashrrev_i32_e32 v247, 31, v246
	v_ashrrev_i32_e32 v251, 31, v250
	v_lshlrev_b64 v[246:247], 1, v[246:247]
	v_lshlrev_b64 v[248:249], 1, v[250:251]
	v_lshrrev_b32_e32 v255, 4, v245
	v_lshrrev_b32_e32 v254, 3, v245
	v_xor_b32_e32 v255, v255, v245
	v_mul_lo_u32 v254, v254, s76
	v_lshlrev_b32_e32 v255, 3, v255
	v_and_or_b32 v254, v255, 56, v254
	v_ashrrev_i32_e32 v255, 31, v254
	v_lshlrev_b64 v[250:251], 1, v[254:255]
	s_mov_b32 s23, s17
	s_mov_b32 s17, s0
	s_add_i32 s71, 0, 0x10000
	ds_read_b128 v[66:69], v174 offset:49152
	ds_read_b128 v[70:73], v174 offset:57344
	ds_read_b128 v[206:209], v176 offset:49152
	ds_read_b128 v[210:213], v176 offset:57344
	s_waitcnt lgkmcnt(0)
	v_mfma_f32_32x32x16_bf16 v[82:97], v[66:69], v[142:145], 0
	s_add_i32 s0, 0, 0x16000
	v_exp_f32_e32 v240, v146
	v_add_f32_e32 v146, 0, v229
	v_add_f32_e32 v146, v231, v146
	v_add_f32_e32 v146, v227, v146
	v_add_f32_e32 v146, v230, v146
	v_add_f32_e32 v146, v226, v146
	v_mfma_f32_32x32x16_bf16 v[66:81], v[70:73], v[142:145], 0
	v_add_f32_e32 v146, v228, v146
	v_add_f32_e32 v146, v224, v146
	v_add_f32_e32 v146, v225, v146
	v_add_f32_e32 v146, v221, v146
	v_add_f32_e32 v146, v223, v146
	v_add_f32_e32 v146, v220, v146
	v_add_f32_e32 v146, v222, v146
	v_mfma_f32_32x32x16_bf16 v[82:97], v[206:209], v[138:141], v[82:97]
	v_exp_f32_e32 v164, v164
	v_add_f32_e32 v146, v217, v146
	v_exp_f32_e32 v165, v165
	v_add_f32_e32 v146, v219, v146
	v_exp_f32_e32 v197, v162
	v_add_f32_e32 v146, v216, v146
	v_add_f32_e32 v146, v218, v146
	v_mfma_f32_32x32x16_bf16 v[66:81], v[210:213], v[138:141], v[66:81]
	ds_read_b128 v[206:209], v178 offset:49152
	ds_read_b128 v[210:213], v178 offset:57344
	s_add_u32 s4, s38, s20
	s_addc_u32 s5, s39, s21
	s_add_u32 s24, s4, 0x149ec400
	s_addc_u32 s25, s5, 0
	s_mov_b32 m0, s90
	v_lshl_add_u64 v[254:255], v[246:247], 0, s[24:25]
	s_lshl_b32 s18, s22, 14
	global_load_lds_dwordx4 v[254:255], off
	s_add_u32 s24, s4, 0x14a0c400
	s_addc_u32 s25, s5, 0
	s_mov_b32 m0, s91
	v_lshl_add_u64 v[254:255], v[246:247], 0, s[24:25]
	s_add_i32 s1, s89, s18
	global_load_lds_dwordx4 v[254:255], off
	s_add_u32 s24, s4, 0x149ec500
	s_addc_u32 s25, s5, 0
	s_mov_b32 m0, s1
	v_lshl_add_u64 v[254:255], v[248:249], 0, s[24:25]
	global_load_lds_dwordx4 v[254:255], off
	s_add_u32 s24, s4, 0x14a0c500
	s_addc_u32 s25, s5, 0
	s_add_i32 m0, s1, 0x2000
	v_lshl_add_u64 v[254:255], v[248:249], 0, s[24:25]
	global_load_lds_dwordx4 v[254:255], off
	s_add_u32 s4, s38, s88
	s_addc_u32 s5, s39, s87
	s_add_u32 s4, s4, s36
	s_addc_u32 s5, s5, s37
	s_mov_b32 m0, s92
	v_lshl_add_u64 v[254:255], v[250:251], 0, s[4:5]
	global_load_lds_dwordx4 v[254:255], off
	v_exp_f32_e32 v156, v156
	v_add_f32_e32 v146, v164, v146
	v_exp_f32_e32 v157, v157
	v_add_f32_e32 v146, v165, v146
	v_add_f32_e32 v146, v197, v146
	v_exp_f32_e32 v241, v147
	s_waitcnt lgkmcnt(0)
	v_mfma_f32_32x32x16_bf16 v[82:97], v[206:209], v[134:137], v[82:97]
	v_mfma_f32_32x32x16_bf16 v[66:81], v[210:213], v[134:137], v[66:81]
	ds_read_b128 v[208:211], v180 offset:49152
	ds_read_b128 v[212:215], v180 offset:57344
	s_waitcnt lgkmcnt(0)
	v_mfma_f32_32x32x16_bf16 v[82:97], v[208:211], v[130:133], v[82:97]
	v_mfma_f32_32x32x16_bf16 v[66:81], v[212:215], v[130:133], v[66:81]
	ds_read_b128 v[208:211], v182 offset:49152
	ds_read_b128 v[212:215], v182 offset:57344
	s_waitcnt lgkmcnt(0)
	v_mfma_f32_32x32x16_bf16 v[82:97], v[208:211], v[126:129], v[82:97]
	v_mfma_f32_32x32x16_bf16 v[66:81], v[212:215], v[126:129], v[66:81]
	ds_read_b128 v[210:213], v186 offset:49152
	ds_read_b128 v[232:235], v186 offset:57344
	s_waitcnt lgkmcnt(0)
	v_mfma_f32_32x32x16_bf16 v[82:97], v[210:213], v[122:125], v[82:97]
	v_mfma_f32_32x32x16_bf16 v[66:81], v[232:235], v[122:125], v[66:81]
	ds_read_b128 v[210:213], v188 offset:49152
	ds_read_b128 v[232:235], v188 offset:57344
	s_waitcnt lgkmcnt(0)
	v_mfma_f32_32x32x16_bf16 v[82:97], v[210:213], v[118:121], v[82:97]
	v_mfma_f32_32x32x16_bf16 v[66:81], v[232:235], v[118:121], v[66:81]
	ds_read_b128 v[212:215], v190 offset:49152
	ds_read_b128 v[232:235], v190 offset:57344
	s_waitcnt lgkmcnt(0)
	v_mfma_f32_32x32x16_bf16 v[82:97], v[212:215], v[114:117], v[82:97]
	v_mfma_f32_32x32x16_bf16 v[66:81], v[232:235], v[114:117], v[66:81]
	ds_read_b128 v[212:215], v192 offset:8192
	ds_read_b128 v[232:235], v192 offset:12288
	s_waitcnt lgkmcnt(0)
	v_mfma_f32_32x32x16_bf16 v[82:97], v[212:215], v[110:113], v[82:97]
	v_exp_f32_e32 v215, v163
	s_nop 0
	v_add_f32_e32 v146, v215, v146
	v_mfma_f32_32x32x16_bf16 v[66:81], v[232:235], v[110:113], v[66:81]
	ds_read_b128 v[232:235], v194 offset:8192
	ds_read_b128 v[236:239], v194 offset:12288
	v_add_f32_e32 v146, v156, v146
	v_add_f32_e32 v146, v157, v146
	s_waitcnt lgkmcnt(0)
	v_mfma_f32_32x32x16_bf16 v[82:97], v[232:235], v[106:109], v[82:97]
	v_mfma_f32_32x32x16_bf16 v[66:81], v[236:239], v[106:109], v[66:81]
	ds_read_b128 v[232:235], v196 offset:8192
	ds_read_b128 v[236:239], v196 offset:12288
	s_waitcnt lgkmcnt(0)
	v_mfma_f32_32x32x16_bf16 v[82:97], v[232:235], v[102:105], v[82:97]
	v_mfma_f32_32x32x16_bf16 v[66:81], v[236:239], v[102:105], v[66:81]
	ds_read_b128 v[232:235], v199 offset:8192
	ds_read_b128 v[236:239], v199 offset:12288
	s_waitcnt lgkmcnt(0)
	v_mfma_f32_32x32x16_bf16 v[82:97], v[232:235], v[98:101], v[82:97]
	v_exp_f32_e32 v232, v154
	v_exp_f32_e32 v233, v155
	v_exp_f32_e32 v234, v152
	v_exp_f32_e32 v235, v153
	v_add_f32_e32 v146, v232, v146
	v_add_f32_e32 v146, v233, v146
	v_add_f32_e32 v146, v234, v146
	v_mfma_f32_32x32x16_bf16 v[66:81], v[236:239], v[98:101], v[66:81]
	v_exp_f32_e32 v236, v150
	v_exp_f32_e32 v237, v151
	v_exp_f32_e32 v238, v148
	v_exp_f32_e32 v239, v149
	v_add_f32_e32 v146, v235, v146
	v_add_f32_e32 v146, v236, v146
	v_add_f32_e32 v146, v237, v146
	v_add_f32_e32 v146, v238, v146
	v_add_f32_e32 v146, v239, v146
	v_add_f32_e32 v146, v240, v146
	v_add_f32_e32 v162, v241, v146
	v_mov_b32_e32 v163, v162
	s_nop 1
	v_permlane32_swap_b32_e32 v162, v163
	v_cvt_pk_bf16_f32 v146, v229, v231
	v_cvt_pk_bf16_f32 v147, v227, v230
	v_cvt_pk_bf16_f32 v148, v226, v228
	v_cvt_pk_bf16_f32 v149, v224, v225
	v_cvt_pk_bf16_f32 v150, v221, v223
	v_cvt_pk_bf16_f32 v151, v220, v222
	v_cvt_pk_bf16_f32 v152, v217, v219
	v_cvt_pk_bf16_f32 v153, v216, v218
	v_cvt_pk_bf16_f32 v154, v164, v165
	v_cvt_pk_bf16_f32 v155, v197, v215
	v_cvt_pk_bf16_f32 v156, v156, v157
	v_cvt_pk_bf16_f32 v157, v232, v233
	v_cvt_pk_bf16_f32 v216, v234, v235
	v_cvt_pk_bf16_f32 v217, v236, v237
	v_cvt_pk_bf16_f32 v218, v238, v239
	v_cvt_pk_bf16_f32 v219, v240, v241
	s_nop 0
	v_permlane32_swap_b32_e32 v146, v148
	v_permlane32_swap_b32_e32 v147, v149
	v_permlane32_swap_b32_e32 v150, v152
	v_permlane32_swap_b32_e32 v151, v153
	v_permlane32_swap_b32_e32 v154, v156
	v_permlane32_swap_b32_e32 v155, v157
	v_permlane32_swap_b32_e32 v216, v218
	v_permlane32_swap_b32_e32 v217, v219
	s_lshl_b32 s24, s17, 14
	v_add_u32_e32 v197, s24, v200
	ds_read_b64_tr_b16 v[220:221], v197 offset:0
	ds_read_b64_tr_b16 v[222:223], v197 offset:0x800
	ds_read_b64_tr_b16 v[224:225], v197 offset:0x1000
	ds_read_b64_tr_b16 v[226:227], v197 offset:0x1800
	ds_read_b64_tr_b16 v[228:229], v197 offset:0x2000
	ds_read_b64_tr_b16 v[230:231], v197 offset:0x2800
	ds_read_b64_tr_b16 v[232:233], v197 offset:0x3000
	ds_read_b64_tr_b16 v[234:235], v197 offset:0x3800
	s_nop 0
	s_waitcnt lgkmcnt(6)
	v_mfma_f32_32x32x16_bf16 v[2:17], v[146:149], v[220:223], v[2:17]
	ds_read_b64_tr_b16 v[220:221], v197 offset:0x200
	ds_read_b64_tr_b16 v[222:223], v197 offset:0xa00
	v_max_f32_e32 v164, v83, v83
	v_max_f32_e32 v165, v82, v82
	v_max_f32_e32 v164, v165, v164
	v_max3_f32 v164, v164, v84, v85
	v_max3_f32 v164, v164, v86, v87
	s_waitcnt lgkmcnt(6)
	v_mfma_f32_32x32x16_bf16 v[2:17], v[150:153], v[224:227], v[2:17]
	ds_read_b64_tr_b16 v[224:225], v197 offset:0x1200
	ds_read_b64_tr_b16 v[226:227], v197 offset:0x1a00
	v_max3_f32 v164, v164, v88, v89
	v_max3_f32 v164, v164, v90, v91
	v_max3_f32 v164, v164, v92, v93
	v_max3_f32 v164, v164, v94, v95
	v_max3_f32 v164, v164, v96, v97
	s_waitcnt lgkmcnt(6)
	v_mfma_f32_32x32x16_bf16 v[2:17], v[154:157], v[228:231], v[2:17]
	ds_read_b64_tr_b16 v[228:229], v197 offset:0x2200
	ds_read_b64_tr_b16 v[230:231], v197 offset:0x2a00
	ds_read_b64_tr_b16 v[236:237], v197 offset:0x3200
	ds_read_b64_tr_b16 v[238:239], v197 offset:0x3a00
	s_waitcnt lgkmcnt(8)
	v_mfma_f32_32x32x16_bf16 v[2:17], v[216:219], v[232:235], v[2:17]
	s_waitcnt lgkmcnt(6)
	v_mfma_f32_32x32x16_bf16 v[50:65], v[146:149], v[220:223], v[50:65]
	v_max3_f32 v164, v164, v66, v67
	v_max3_f32 v164, v164, v68, v69
	v_max3_f32 v164, v164, v70, v71
	v_max3_f32 v164, v164, v72, v73
	v_max3_f32 v164, v164, v74, v75
	v_max3_f32 v164, v164, v76, v77
	v_max3_f32 v164, v164, v78, v79
	s_waitcnt lgkmcnt(4)
	v_mfma_f32_32x32x16_bf16 v[50:65], v[150:153], v[224:227], v[50:65]
	v_max3_f32 v164, v164, v80, v81
	v_mov_b32_e32 v165, v164
	s_nop 1
	v_permlane32_swap_b32_e32 v164, v165
	ds_read_b64_tr_b16 v[220:221], v197 offset:0x400
	v_max_f32_e32 v165, v165, v165
	v_max_f32_e32 v164, v164, v164
	s_waitcnt lgkmcnt(3)
	v_mfma_f32_32x32x16_bf16 v[50:65], v[154:157], v[228:231], v[50:65]
	ds_read_b64_tr_b16 v[222:223], v197 offset:0xc00
	v_max_f32_e32 v164, v164, v165
	v_max_f32_e32 v165, v202, v202
	ds_read_b64_tr_b16 v[224:225], v197 offset:0x1400
	v_max_f32_e32 v165, v165, v164
	ds_read_b64_tr_b16 v[226:227], v197 offset:0x1c00
	v_sub_f32_e32 v215, v164, v202
	s_waitcnt lgkmcnt(4)
	v_mfma_f32_32x32x16_bf16 v[50:65], v[216:219], v[236:239], v[50:65]
	v_sub_f32_e32 v164, v202, v165
	ds_read_b64_tr_b16 v[228:229], v197 offset:0x2400
	v_mul_f32_e32 v164, 0x3dd53b94, v164
	ds_read_b64_tr_b16 v[230:231], v197 offset:0x2c00
	v_exp_f32_e32 v164, v164
	ds_read_b64_tr_b16 v[232:233], v197 offset:0x3400
	v_cmp_ge_f32_e32 vcc, s77, v215
	ds_read_b64_tr_b16 v[234:235], v197 offset:0x3c00
	s_cmp_eq_u64 vcc, exec
	s_cselect_b64 s[4:5], -1, 0
	v_cndmask_b32_e64 v164, v164, 1.0, s[4:5]
	s_waitcnt lgkmcnt(6)
	v_mfma_f32_32x32x16_bf16 v[34:49], v[146:149], v[220:223], v[34:49]
	ds_read_b64_tr_b16 v[220:221], v197 offset:0x600
	ds_read_b64_tr_b16 v[222:223], v197 offset:0xe00
	s_waitcnt lgkmcnt(6)
	v_mfma_f32_32x32x16_bf16 v[34:49], v[150:153], v[224:227], v[34:49]
	ds_read_b64_tr_b16 v[224:225], v197 offset:0x1600
	ds_read_b64_tr_b16 v[226:227], v197 offset:0x1e00
	s_waitcnt lgkmcnt(6)
	v_mfma_f32_32x32x16_bf16 v[34:49], v[154:157], v[228:231], v[34:49]
	ds_read_b64_tr_b16 v[228:229], v197 offset:0x2600
	ds_read_b64_tr_b16 v[230:231], v197 offset:0x2e00
	ds_read_b64_tr_b16 v[236:237], v197 offset:0x3600
	ds_read_b64_tr_b16 v[238:239], v197 offset:0x3e00
	s_waitcnt lgkmcnt(8)
	v_mfma_f32_32x32x16_bf16 v[34:49], v[216:219], v[232:235], v[34:49]
	s_waitcnt lgkmcnt(6)
	v_mfma_f32_32x32x16_bf16 v[18:33], v[146:149], v[220:223], v[18:33]
	v_cmp_gt_f32_e32 vcc, 1.0, v164
	s_waitcnt lgkmcnt(4)
	v_mfma_f32_32x32x16_bf16 v[18:33], v[150:153], v[224:227], v[18:33]
	s_waitcnt lgkmcnt(2)
	v_mfma_f32_32x32x16_bf16 v[18:33], v[154:157], v[228:231], v[18:33]
	s_waitcnt lgkmcnt(0)
	v_mfma_f32_32x32x16_bf16 v[18:33], v[216:219], v[236:239], v[18:33]
	s_cbranch_vccz .Lmla_e_547
	s_and_saveexec_b64 s[0:1], s[2:3]
	ds_write_b32 v170, v164 offset:128
	s_or_b64 exec, exec, s[0:1]
	s_waitcnt lgkmcnt(0)
	ds_read_b128 v[146:149], v158 offset:224
	ds_read_b128 v[150:153], v158 offset:192
	ds_read_b128 v[154:157], v158 offset:160
	ds_read_b128 v[216:219], v158 offset:128
	s_waitcnt lgkmcnt(0)
	v_pk_mul_f32 v[16:17], v[16:17], v[148:149]
	v_pk_mul_f32 v[12:13], v[12:13], v[152:153]
	v_pk_mul_f32 v[8:9], v[8:9], v[156:157]
	v_pk_mul_f32 v[4:5], v[4:5], v[218:219]
	v_pk_mul_f32 v[14:15], v[14:15], v[146:147]
	v_pk_mul_f32 v[10:11], v[10:11], v[150:151]
	v_pk_mul_f32 v[6:7], v[6:7], v[154:155]
	v_pk_mul_f32 v[2:3], v[2:3], v[216:217]
	v_pk_mul_f32 v[64:65], v[64:65], v[148:149]
	v_pk_mul_f32 v[60:61], v[60:61], v[152:153]
	v_pk_mul_f32 v[56:57], v[56:57], v[156:157]
	v_pk_mul_f32 v[52:53], v[52:53], v[218:219]
	v_pk_mul_f32 v[62:63], v[62:63], v[146:147]
	v_pk_mul_f32 v[58:59], v[58:59], v[150:151]
	v_pk_mul_f32 v[54:55], v[54:55], v[154:155]
	v_pk_mul_f32 v[50:51], v[50:51], v[216:217]
	v_pk_mul_f32 v[48:49], v[48:49], v[148:149]
	v_pk_mul_f32 v[44:45], v[44:45], v[152:153]
	v_pk_mul_f32 v[40:41], v[40:41], v[156:157]
	v_pk_mul_f32 v[36:37], v[36:37], v[218:219]
	v_pk_mul_f32 v[46:47], v[46:47], v[146:147]
	v_pk_mul_f32 v[42:43], v[42:43], v[150:151]
	v_pk_mul_f32 v[38:39], v[38:39], v[154:155]
	v_pk_mul_f32 v[34:35], v[34:35], v[216:217]
	v_pk_mul_f32 v[32:33], v[32:33], v[148:149]
	v_pk_mul_f32 v[28:29], v[28:29], v[152:153]
	v_pk_mul_f32 v[24:25], v[24:25], v[156:157]
	v_pk_mul_f32 v[20:21], v[20:21], v[218:219]
	v_pk_mul_f32 v[30:31], v[30:31], v[146:147]
	v_pk_mul_f32 v[26:27], v[26:27], v[150:151]
	v_pk_mul_f32 v[22:23], v[22:23], v[154:155]
	v_pk_mul_f32 v[18:19], v[18:19], v[216:217]

.LBB0_543:
	s_mov_b32 s23, s17
	s_mov_b32 s17, s0
	s_add_i32 s71, 0, 0x10000
	ds_read_b128 v[66:69], v174 offset:49152
	ds_read_b128 v[70:73], v174 offset:57344
	ds_read_b128 v[206:209], v176 offset:49152
	ds_read_b128 v[210:213], v176 offset:57344
	v_fma_f32 v152, v74, s34, v146
	v_fma_f32 v153, v75, s34, v146
	v_fma_f32 v150, v76, s34, v146
	v_fma_f32 v151, v77, s34, v146
	v_fma_f32 v148, v78, s34, v146
	v_fma_f32 v149, v79, s34, v146
	v_fma_f32 v147, v81, s34, v146
	v_fma_f32 v146, v80, s34, v146
	v_exp_f32_e32 v229, v229
	v_exp_f32_e32 v231, v231
	v_exp_f32_e32 v227, v227
	v_exp_f32_e32 v230, v230
	v_exp_f32_e32 v226, v226
	v_exp_f32_e32 v228, v228
	s_waitcnt lgkmcnt(0)
	v_mfma_f32_32x32x16_bf16 v[82:97], v[66:69], v[142:145], 0
	s_add_i32 s0, 0, 0x16000
	v_exp_f32_e32 v240, v146
	v_add_f32_e32 v146, 0, v229
	v_add_f32_e32 v146, v231, v146
	v_add_f32_e32 v146, v227, v146
	v_add_f32_e32 v146, v230, v146
	v_add_f32_e32 v146, v226, v146
	v_exp_f32_e32 v224, v224
	v_exp_f32_e32 v225, v225
	v_exp_f32_e32 v221, v221
	v_exp_f32_e32 v223, v223
	v_mfma_f32_32x32x16_bf16 v[66:81], v[70:73], v[142:145], 0
	v_exp_f32_e32 v220, v220
	v_exp_f32_e32 v222, v222
	v_add_f32_e32 v146, v228, v146
	v_add_f32_e32 v146, v224, v146
	v_add_f32_e32 v146, v225, v146
	v_add_f32_e32 v146, v221, v146
	v_add_f32_e32 v146, v223, v146
	v_add_f32_e32 v146, v220, v146
	v_add_f32_e32 v146, v222, v146
	v_exp_f32_e32 v217, v217
	v_exp_f32_e32 v219, v219
	v_exp_f32_e32 v216, v216
	v_exp_f32_e32 v218, v218
	v_mfma_f32_32x32x16_bf16 v[82:97], v[206:209], v[138:141], v[82:97]
	v_exp_f32_e32 v164, v164
	v_add_f32_e32 v146, v217, v146
	v_exp_f32_e32 v165, v165
	v_add_f32_e32 v146, v219, v146
	v_exp_f32_e32 v197, v162
	v_add_f32_e32 v146, v216, v146
	v_add_f32_e32 v146, v218, v146
	v_mfma_f32_32x32x16_bf16 v[66:81], v[210:213], v[138:141], v[66:81]
	ds_read_b128 v[206:209], v178 offset:49152
	ds_read_b128 v[210:213], v178 offset:57344
	s_add_u32 s4, s38, s20
	s_addc_u32 s5, s39, s21
	s_add_u32 s24, s4, 0x149ec400
	s_addc_u32 s25, s5, 0
	s_mov_b32 m0, s90
	v_lshl_add_u64 v[254:255], v[246:247], 0, s[24:25]
	s_lshl_b32 s18, s22, 14
	global_load_lds_dwordx4 v[254:255], off
	s_add_u32 s24, s4, 0x14a0c400
	s_addc_u32 s25, s5, 0
	s_mov_b32 m0, s91
	v_lshl_add_u64 v[254:255], v[246:247], 0, s[24:25]
	s_add_i32 s1, s89, s18
	global_load_lds_dwordx4 v[254:255], off
	s_add_u32 s24, s4, 0x149ec500
	s_addc_u32 s25, s5, 0
	s_mov_b32 m0, s1
	v_lshl_add_u64 v[254:255], v[248:249], 0, s[24:25]
	global_load_lds_dwordx4 v[254:255], off
	s_add_u32 s24, s4, 0x14a0c500
	s_addc_u32 s25, s5, 0
	s_add_i32 m0, s1, 0x2000
	v_lshl_add_u64 v[254:255], v[248:249], 0, s[24:25]
	global_load_lds_dwordx4 v[254:255], off
	s_add_u32 s4, s38, s88
	s_addc_u32 s5, s39, s87
	s_add_u32 s4, s4, s36
	s_addc_u32 s5, s5, s37
	s_mov_b32 m0, s92
	v_lshl_add_u64 v[254:255], v[250:251], 0, s[4:5]
	global_load_lds_dwordx4 v[254:255], off
	v_exp_f32_e32 v156, v156
	v_add_f32_e32 v146, v164, v146
	v_exp_f32_e32 v157, v157
	v_add_f32_e32 v146, v165, v146
	v_add_f32_e32 v146, v197, v146
	v_exp_f32_e32 v241, v147
	s_waitcnt lgkmcnt(0)
	v_mfma_f32_32x32x16_bf16 v[82:97], v[206:209], v[134:137], v[82:97]
	v_mfma_f32_32x32x16_bf16 v[66:81], v[210:213], v[134:137], v[66:81]
	ds_read_b128 v[208:211], v180 offset:49152
	ds_read_b128 v[212:215], v180 offset:57344
	s_waitcnt lgkmcnt(0)
	v_mfma_f32_32x32x16_bf16 v[82:97], v[208:211], v[130:133], v[82:97]
	v_mfma_f32_32x32x16_bf16 v[66:81], v[212:215], v[130:133], v[66:81]
	ds_read_b128 v[208:211], v182 offset:49152
	ds_read_b128 v[212:215], v182 offset:57344
	s_waitcnt lgkmcnt(0)
	v_mfma_f32_32x32x16_bf16 v[82:97], v[208:211], v[126:129], v[82:97]
	v_mfma_f32_32x32x16_bf16 v[66:81], v[212:215], v[126:129], v[66:81]
	ds_read_b128 v[210:213], v186 offset:49152
	ds_read_b128 v[232:235], v186 offset:57344
	s_waitcnt lgkmcnt(0)
	v_mfma_f32_32x32x16_bf16 v[82:97], v[210:213], v[122:125], v[82:97]
	v_mfma_f32_32x32x16_bf16 v[66:81], v[232:235], v[122:125], v[66:81]
	ds_read_b128 v[210:213], v188 offset:49152
	ds_read_b128 v[232:235], v188 offset:57344
	s_waitcnt lgkmcnt(0)
	v_mfma_f32_32x32x16_bf16 v[82:97], v[210:213], v[118:121], v[82:97]
	v_mfma_f32_32x32x16_bf16 v[66:81], v[232:235], v[118:121], v[66:81]
	ds_read_b128 v[212:215], v190 offset:49152
	ds_read_b128 v[232:235], v190 offset:57344
	s_waitcnt lgkmcnt(0)
	v_mfma_f32_32x32x16_bf16 v[82:97], v[212:215], v[114:117], v[82:97]
	v_mfma_f32_32x32x16_bf16 v[66:81], v[232:235], v[114:117], v[66:81]
	ds_read_b128 v[212:215], v192 offset:8192
	ds_read_b128 v[232:235], v192 offset:12288
	s_waitcnt lgkmcnt(0)
	v_mfma_f32_32x32x16_bf16 v[82:97], v[212:215], v[110:113], v[82:97]
	v_exp_f32_e32 v215, v163
	s_nop 0
	v_add_f32_e32 v146, v215, v146
	v_mfma_f32_32x32x16_bf16 v[66:81], v[232:235], v[110:113], v[66:81]
	ds_read_b128 v[232:235], v194 offset:8192
	ds_read_b128 v[236:239], v194 offset:12288
	v_add_f32_e32 v146, v156, v146
	v_add_f32_e32 v146, v157, v146
	s_waitcnt lgkmcnt(0)
	v_mfma_f32_32x32x16_bf16 v[82:97], v[232:235], v[106:109], v[82:97]
	v_mfma_f32_32x32x16_bf16 v[66:81], v[236:239], v[106:109], v[66:81]
	ds_read_b128 v[232:235], v196 offset:8192
	ds_read_b128 v[236:239], v196 offset:12288
	s_waitcnt lgkmcnt(0)
	v_mfma_f32_32x32x16_bf16 v[82:97], v[232:235], v[102:105], v[82:97]
	v_mfma_f32_32x32x16_bf16 v[66:81], v[236:239], v[102:105], v[66:81]
	ds_read_b128 v[232:235], v199 offset:8192
	ds_read_b128 v[236:239], v199 offset:12288
	s_waitcnt lgkmcnt(0)
	v_mfma_f32_32x32x16_bf16 v[82:97], v[232:235], v[98:101], v[82:97]
	v_exp_f32_e32 v232, v154
	v_exp_f32_e32 v233, v155
	v_exp_f32_e32 v234, v152
	v_exp_f32_e32 v235, v153
	v_add_f32_e32 v146, v232, v146
	v_add_f32_e32 v146, v233, v146
	v_add_f32_e32 v146, v234, v146
	v_mfma_f32_32x32x16_bf16 v[66:81], v[236:239], v[98:101], v[66:81]
	v_exp_f32_e32 v236, v150
	v_exp_f32_e32 v237, v151
	v_exp_f32_e32 v238, v148
	v_exp_f32_e32 v239, v149
	v_add_f32_e32 v146, v235, v146
	v_add_f32_e32 v146, v236, v146
	v_add_f32_e32 v146, v237, v146
	v_add_f32_e32 v146, v238, v146
	v_add_f32_e32 v146, v239, v146
	v_add_f32_e32 v146, v240, v146
	v_add_f32_e32 v162, v241, v146
	v_mov_b32_e32 v163, v162
	s_nop 1
	v_permlane32_swap_b32_e32 v162, v163
	v_cvt_pk_bf16_f32 v146, v229, v231
	v_cvt_pk_bf16_f32 v147, v227, v230
	v_cvt_pk_bf16_f32 v148, v226, v228
	v_cvt_pk_bf16_f32 v149, v224, v225
	v_cvt_pk_bf16_f32 v150, v221, v223
	v_cvt_pk_bf16_f32 v151, v220, v222
	v_cvt_pk_bf16_f32 v152, v217, v219
	v_cvt_pk_bf16_f32 v153, v216, v218
	v_cvt_pk_bf16_f32 v154, v164, v165
	v_cvt_pk_bf16_f32 v155, v197, v215
	v_cvt_pk_bf16_f32 v156, v156, v157
	v_cvt_pk_bf16_f32 v157, v232, v233
	v_cvt_pk_bf16_f32 v216, v234, v235
	v_cvt_pk_bf16_f32 v217, v236, v237
	v_cvt_pk_bf16_f32 v218, v238, v239
	v_cvt_pk_bf16_f32 v219, v240, v241
	s_nop 0
	v_permlane32_swap_b32_e32 v146, v148
	v_permlane32_swap_b32_e32 v147, v149
	v_permlane32_swap_b32_e32 v150, v152
	v_permlane32_swap_b32_e32 v151, v153
	v_permlane32_swap_b32_e32 v154, v156
	v_permlane32_swap_b32_e32 v155, v157
	v_permlane32_swap_b32_e32 v216, v218
	v_permlane32_swap_b32_e32 v217, v219
	s_lshl_b32 s24, s17, 14
	v_add_u32_e32 v197, s24, v200
	ds_read_b64_tr_b16 v[220:221], v197 offset:0
	ds_read_b64_tr_b16 v[222:223], v197 offset:0x800
	ds_read_b64_tr_b16 v[224:225], v197 offset:0x1000
	ds_read_b64_tr_b16 v[226:227], v197 offset:0x1800
	ds_read_b64_tr_b16 v[228:229], v197 offset:0x2000
	ds_read_b64_tr_b16 v[230:231], v197 offset:0x2800
	ds_read_b64_tr_b16 v[232:233], v197 offset:0x3000
	ds_read_b64_tr_b16 v[234:235], v197 offset:0x3800
	s_nop 0
	s_waitcnt lgkmcnt(6)
	v_mfma_f32_32x32x16_bf16 v[2:17], v[146:149], v[220:223], v[2:17]
	ds_read_b64_tr_b16 v[220:221], v197 offset:0x200
	ds_read_b64_tr_b16 v[222:223], v197 offset:0xa00
	v_max_f32_e32 v164, v83, v83
	v_max_f32_e32 v165, v82, v82
	v_max_f32_e32 v164, v165, v164
	v_max3_f32 v164, v164, v84, v85
	v_max3_f32 v164, v164, v86, v87
	s_waitcnt lgkmcnt(6)
	v_mfma_f32_32x32x16_bf16 v[2:17], v[150:153], v[224:227], v[2:17]
	ds_read_b64_tr_b16 v[224:225], v197 offset:0x1200
	ds_read_b64_tr_b16 v[226:227], v197 offset:0x1a00
	v_max3_f32 v164, v164, v88, v89
	v_max3_f32 v164, v164, v90, v91
	v_max3_f32 v164, v164, v92, v93
	v_max3_f32 v164, v164, v94, v95
	v_max3_f32 v164, v164, v96, v97
	s_waitcnt lgkmcnt(6)
	v_mfma_f32_32x32x16_bf16 v[2:17], v[154:157], v[228:231], v[2:17]
	ds_read_b64_tr_b16 v[228:229], v197 offset:0x2200
	ds_read_b64_tr_b16 v[230:231], v197 offset:0x2a00
	ds_read_b64_tr_b16 v[236:237], v197 offset:0x3200
	ds_read_b64_tr_b16 v[238:239], v197 offset:0x3a00
	s_waitcnt lgkmcnt(8)
	v_mfma_f32_32x32x16_bf16 v[2:17], v[216:219], v[232:235], v[2:17]
	s_waitcnt lgkmcnt(6)
	v_mfma_f32_32x32x16_bf16 v[50:65], v[146:149], v[220:223], v[50:65]
	v_max3_f32 v164, v164, v66, v67
	v_max3_f32 v164, v164, v68, v69
	v_max3_f32 v164, v164, v70, v71
	v_max3_f32 v164, v164, v72, v73
	v_max3_f32 v164, v164, v74, v75
	v_max3_f32 v164, v164, v76, v77
	v_max3_f32 v164, v164, v78, v79
	s_waitcnt lgkmcnt(4)
	v_mfma_f32_32x32x16_bf16 v[50:65], v[150:153], v[224:227], v[50:65]
	v_max3_f32 v164, v164, v80, v81
	v_mov_b32_e32 v165, v164
	s_nop 1
	v_permlane32_swap_b32_e32 v164, v165
	ds_read_b64_tr_b16 v[220:221], v197 offset:0x400
	v_max_f32_e32 v165, v165, v165
	v_max_f32_e32 v164, v164, v164
	s_waitcnt lgkmcnt(3)
	v_mfma_f32_32x32x16_bf16 v[50:65], v[154:157], v[228:231], v[50:65]
	ds_read_b64_tr_b16 v[222:223], v197 offset:0xc00
	v_max_f32_e32 v164, v164, v165
	v_max_f32_e32 v165, v202, v202
	ds_read_b64_tr_b16 v[224:225], v197 offset:0x1400
	v_max_f32_e32 v165, v165, v164
	ds_read_b64_tr_b16 v[226:227], v197 offset:0x1c00
	v_sub_f32_e32 v215, v164, v202
	s_waitcnt lgkmcnt(4)
	v_mfma_f32_32x32x16_bf16 v[50:65], v[216:219], v[236:239], v[50:65]
	v_sub_f32_e32 v164, v202, v165
	ds_read_b64_tr_b16 v[228:229], v197 offset:0x2400
	v_mul_f32_e32 v164, 0x3dd53b94, v164
	ds_read_b64_tr_b16 v[230:231], v197 offset:0x2c00
	v_exp_f32_e32 v164, v164
	ds_read_b64_tr_b16 v[232:233], v197 offset:0x3400
	v_cmp_ge_f32_e32 vcc, s77, v215
	ds_read_b64_tr_b16 v[234:235], v197 offset:0x3c00
	s_cmp_eq_u64 vcc, exec
	s_cselect_b64 s[4:5], -1, 0
	v_cndmask_b32_e64 v164, v164, 1.0, s[4:5]
	s_waitcnt lgkmcnt(6)
	v_mfma_f32_32x32x16_bf16 v[34:49], v[146:149], v[220:223], v[34:49]
	ds_read_b64_tr_b16 v[220:221], v197 offset:0x600
	ds_read_b64_tr_b16 v[222:223], v197 offset:0xe00
	s_waitcnt lgkmcnt(6)
	v_mfma_f32_32x32x16_bf16 v[34:49], v[150:153], v[224:227], v[34:49]
	ds_read_b64_tr_b16 v[224:225], v197 offset:0x1600
	ds_read_b64_tr_b16 v[226:227], v197 offset:0x1e00
	s_waitcnt lgkmcnt(6)
	v_mfma_f32_32x32x16_bf16 v[34:49], v[154:157], v[228:231], v[34:49]
	ds_read_b64_tr_b16 v[228:229], v197 offset:0x2600
	ds_read_b64_tr_b16 v[230:231], v197 offset:0x2e00
	ds_read_b64_tr_b16 v[236:237], v197 offset:0x3600
	ds_read_b64_tr_b16 v[238:239], v197 offset:0x3e00
	s_waitcnt lgkmcnt(8)
	v_mfma_f32_32x32x16_bf16 v[34:49], v[216:219], v[232:235], v[34:49]
	s_waitcnt lgkmcnt(6)
	v_mfma_f32_32x32x16_bf16 v[18:33], v[146:149], v[220:223], v[18:33]
	v_cmp_gt_f32_e32 vcc, 1.0, v164
	s_waitcnt lgkmcnt(4)
	v_mfma_f32_32x32x16_bf16 v[18:33], v[150:153], v[224:227], v[18:33]
	s_waitcnt lgkmcnt(2)
	v_mfma_f32_32x32x16_bf16 v[18:33], v[154:157], v[228:231], v[18:33]
	s_waitcnt lgkmcnt(0)
	v_mfma_f32_32x32x16_bf16 v[18:33], v[216:219], v[236:239], v[18:33]
	s_cbranch_vccz .LBB0_547
	s_and_saveexec_b64 s[0:1], s[2:3]
	ds_write_b32 v170, v164 offset:128
	s_or_b64 exec, exec, s[0:1]
	s_waitcnt lgkmcnt(0)
	ds_read_b128 v[146:149], v158 offset:224
	ds_read_b128 v[150:153], v158 offset:192
	ds_read_b128 v[154:157], v158 offset:160
	ds_read_b128 v[216:219], v158 offset:128
	s_waitcnt lgkmcnt(0)
	v_pk_mul_f32 v[16:17], v[16:17], v[148:149]
	v_pk_mul_f32 v[12:13], v[12:13], v[152:153]
	v_pk_mul_f32 v[8:9], v[8:9], v[156:157]
	v_pk_mul_f32 v[4:5], v[4:5], v[218:219]
	v_pk_mul_f32 v[14:15], v[14:15], v[146:147]
	v_pk_mul_f32 v[10:11], v[10:11], v[150:151]
	v_pk_mul_f32 v[6:7], v[6:7], v[154:155]
	v_pk_mul_f32 v[2:3], v[2:3], v[216:217]
	v_pk_mul_f32 v[64:65], v[64:65], v[148:149]
	v_pk_mul_f32 v[60:61], v[60:61], v[152:153]
	v_pk_mul_f32 v[56:57], v[56:57], v[156:157]
	v_pk_mul_f32 v[52:53], v[52:53], v[218:219]
	v_pk_mul_f32 v[62:63], v[62:63], v[146:147]
	v_pk_mul_f32 v[58:59], v[58:59], v[150:151]
	v_pk_mul_f32 v[54:55], v[54:55], v[154:155]
	v_pk_mul_f32 v[50:51], v[50:51], v[216:217]
	v_pk_mul_f32 v[48:49], v[48:49], v[148:149]
	v_pk_mul_f32 v[44:45], v[44:45], v[152:153]
	v_pk_mul_f32 v[40:41], v[40:41], v[156:157]
	v_pk_mul_f32 v[36:37], v[36:37], v[218:219]
	v_pk_mul_f32 v[46:47], v[46:47], v[146:147]
	v_pk_mul_f32 v[42:43], v[42:43], v[150:151]
	v_pk_mul_f32 v[38:39], v[38:39], v[154:155]
	v_pk_mul_f32 v[34:35], v[34:35], v[216:217]
	v_pk_mul_f32 v[32:33], v[32:33], v[148:149]
	v_pk_mul_f32 v[28:29], v[28:29], v[152:153]
	v_pk_mul_f32 v[24:25], v[24:25], v[156:157]
	v_pk_mul_f32 v[20:21], v[20:21], v[218:219]
	v_pk_mul_f32 v[30:31], v[30:31], v[146:147]
	v_pk_mul_f32 v[26:27], v[26:27], v[150:151]
	v_pk_mul_f32 v[22:23], v[22:23], v[154:155]
	v_pk_mul_f32 v[18:19], v[18:19], v[216:217]

.Lattn_mla_nopf:
	s_waitcnt lgkmcnt(0)
	v_mfma_f32_32x32x16_bf16 v[82:97], v[146:149], v[134:137], v[82:97]
	v_mfma_f32_32x32x16_bf16 v[66:81], v[150:153], v[134:137], v[66:81]
	ds_read_b128 v[146:149], v180 offset:32768
	ds_read_b128 v[150:153], v180 offset:40960
	v_exp_f32_e32 v231, v231
	v_exp_f32_e32 v234, v234
	v_exp_f32_e32 v235, v235
	v_add_f32_e32 v245, v231, v245
	v_add_f32_e32 v245, v234, v245
	v_add_f32_e32 v245, v235, v245
	s_waitcnt lgkmcnt(0)
	v_mfma_f32_32x32x16_bf16 v[82:97], v[146:149], v[130:133], v[82:97]
	v_mfma_f32_32x32x16_bf16 v[66:81], v[150:153], v[130:133], v[66:81]
	ds_read_b128 v[146:149], v182 offset:32768
	ds_read_b128 v[150:153], v182 offset:40960
	v_exp_f32_e32 v236, v236
	v_exp_f32_e32 v237, v237
	v_exp_f32_e32 v238, v238
	v_add_f32_e32 v245, v236, v245
	v_add_f32_e32 v245, v237, v245
	v_add_f32_e32 v245, v238, v245
	s_waitcnt lgkmcnt(0)
	v_mfma_f32_32x32x16_bf16 v[82:97], v[146:149], v[126:129], v[82:97]
	v_mfma_f32_32x32x16_bf16 v[66:81], v[150:153], v[126:129], v[66:81]
	ds_read_b128 v[146:149], v186 offset:32768
	ds_read_b128 v[150:153], v186 offset:40960
	v_exp_f32_e32 v239, v239
	v_exp_f32_e32 v240, v240
	v_exp_f32_e32 v241, v241
	v_add_f32_e32 v245, v239, v245
	v_add_f32_e32 v245, v240, v245
	v_add_f32_e32 v245, v241, v245
	s_waitcnt lgkmcnt(0)
	v_mfma_f32_32x32x16_bf16 v[82:97], v[146:149], v[122:125], v[82:97]
	v_mfma_f32_32x32x16_bf16 v[66:81], v[150:153], v[122:125], v[66:81]
	ds_read_b128 v[146:149], v188 offset:32768
	ds_read_b128 v[150:153], v188 offset:40960
	v_exp_f32_e32 v155, v155
	v_exp_f32_e32 v156, v156
	v_exp_f32_e32 v157, v157
	v_add_f32_e32 v245, v155, v245
	v_add_f32_e32 v245, v156, v245
	v_add_f32_e32 v245, v157, v245
	s_waitcnt lgkmcnt(0)
	v_mfma_f32_32x32x16_bf16 v[82:97], v[146:149], v[118:121], v[82:97]
	v_mfma_f32_32x32x16_bf16 v[66:81], v[150:153], v[118:121], v[66:81]
	ds_read_b128 v[146:149], v190 offset:32768
	ds_read_b128 v[150:153], v190 offset:40960
	v_exp_f32_e32 v202, v202
	v_exp_f32_e32 v215, v215
	v_exp_f32_e32 v216, v216
	v_add_f32_e32 v245, v202, v245
	v_add_f32_e32 v245, v215, v245
	v_add_f32_e32 v245, v216, v245
	s_waitcnt lgkmcnt(0)
	v_mfma_f32_32x32x16_bf16 v[82:97], v[146:149], v[114:117], v[82:97]
	v_mfma_f32_32x32x16_bf16 v[66:81], v[150:153], v[114:117], v[66:81]
	ds_read_b128 v[146:149], v192
	ds_read_b128 v[150:153], v192 offset:4096
	v_exp_f32_e32 v217, v217
	v_exp_f32_e32 v218, v218
	v_exp_f32_e32 v219, v219
	v_add_f32_e32 v245, v217, v245
	v_add_f32_e32 v245, v218, v245
	v_add_f32_e32 v245, v219, v245
	s_waitcnt lgkmcnt(0)
	v_mfma_f32_32x32x16_bf16 v[82:97], v[146:149], v[110:113], v[82:97]
	v_mfma_f32_32x32x16_bf16 v[66:81], v[150:153], v[110:113], v[66:81]
	ds_read_b128 v[146:149], v194
	ds_read_b128 v[150:153], v194 offset:4096
	v_exp_f32_e32 v220, v220
	v_exp_f32_e32 v221, v221
	v_exp_f32_e32 v222, v222
	v_add_f32_e32 v245, v220, v245
	v_add_f32_e32 v245, v221, v245
	v_add_f32_e32 v245, v222, v245
	s_waitcnt lgkmcnt(0)
	v_mfma_f32_32x32x16_bf16 v[82:97], v[146:149], v[106:109], v[82:97]
	v_mfma_f32_32x32x16_bf16 v[66:81], v[150:153], v[106:109], v[66:81]
	ds_read_b128 v[146:149], v196
	ds_read_b128 v[150:153], v196 offset:4096
	v_exp_f32_e32 v223, v223
	v_exp_f32_e32 v242, v232
	v_exp_f32_e32 v243, v233
	v_add_f32_e32 v245, v223, v245
	v_add_f32_e32 v245, v242, v245
	v_add_f32_e32 v245, v243, v245
	s_waitcnt lgkmcnt(0)
	v_mfma_f32_32x32x16_bf16 v[82:97], v[146:149], v[102:105], v[82:97]
	v_mfma_f32_32x32x16_bf16 v[66:81], v[150:153], v[102:105], v[66:81]
	ds_read_b128 v[146:149], v199
	ds_read_b128 v[150:153], v199 offset:4096
	v_exp_f32_e32 v244, v154
	s_waitcnt lgkmcnt(0)
	v_mfma_f32_32x32x16_bf16 v[82:97], v[146:149], v[98:101], v[82:97]
	v_mfma_f32_32x32x16_bf16 v[66:81], v[150:153], v[98:101], v[66:81]
	v_add_f32_e32 v232, v244, v245
	v_mov_b32_e32 v233, v232
	s_nop 1
	v_permlane32_swap_b32_e32 v232, v233
	v_cvt_pk_bf16_f32 v146, v224, v225
	v_cvt_pk_bf16_f32 v147, v226, v227
	v_cvt_pk_bf16_f32 v148, v228, v229
	v_cvt_pk_bf16_f32 v149, v230, v231
	v_cvt_pk_bf16_f32 v150, v234, v235
	v_cvt_pk_bf16_f32 v151, v236, v237
	v_cvt_pk_bf16_f32 v152, v238, v239
	v_cvt_pk_bf16_f32 v153, v240, v241
	v_cvt_pk_bf16_f32 v154, v155, v156
	v_cvt_pk_bf16_f32 v155, v157, v202
	v_cvt_pk_bf16_f32 v156, v215, v216
	v_cvt_pk_bf16_f32 v157, v217, v218
	v_cvt_pk_bf16_f32 v216, v219, v220
	v_cvt_pk_bf16_f32 v217, v221, v222
	v_cvt_pk_bf16_f32 v218, v223, v242
	v_cvt_pk_bf16_f32 v219, v243, v244
	s_nop 0
	v_permlane32_swap_b32_e32 v146, v148
	v_permlane32_swap_b32_e32 v147, v149
	v_permlane32_swap_b32_e32 v150, v152
	v_permlane32_swap_b32_e32 v151, v153
	v_permlane32_swap_b32_e32 v154, v156
	v_permlane32_swap_b32_e32 v155, v157
	v_permlane32_swap_b32_e32 v216, v218
	v_permlane32_swap_b32_e32 v217, v219
	v_lshl_add_u32 v242, s23, 14, v200
	ds_read_b64_tr_b16 v[220:221], v242 offset:0
	ds_read_b64_tr_b16 v[222:223], v242 offset:0x800
	ds_read_b64_tr_b16 v[224:225], v242 offset:0x1000
	ds_read_b64_tr_b16 v[226:227], v242 offset:0x1800
	ds_read_b64_tr_b16 v[228:229], v242 offset:0x2000
	ds_read_b64_tr_b16 v[230:231], v242 offset:0x2800
	ds_read_b64_tr_b16 v[234:235], v242 offset:0x3000
	ds_read_b64_tr_b16 v[236:237], v242 offset:0x3800
	s_nop 0
	s_waitcnt lgkmcnt(6)
	v_mfma_f32_32x32x16_bf16 v[2:17], v[146:149], v[220:223], v[2:17]
	ds_read_b64_tr_b16 v[220:221], v242 offset:0x200
	ds_read_b64_tr_b16 v[222:223], v242 offset:0xa00
	v_max_f32_e32 v202, v83, v83
	v_max_f32_e32 v215, v82, v82
	v_max_f32_e32 v202, v215, v202
	v_max3_f32 v202, v202, v84, v85
	v_max3_f32 v202, v202, v86, v87
	s_waitcnt lgkmcnt(6)
	v_mfma_f32_32x32x16_bf16 v[2:17], v[150:153], v[224:227], v[2:17]
	ds_read_b64_tr_b16 v[224:225], v242 offset:0x1200
	ds_read_b64_tr_b16 v[226:227], v242 offset:0x1a00
	v_max3_f32 v202, v202, v88, v89
	v_max3_f32 v202, v202, v90, v91
	v_max3_f32 v202, v202, v92, v93
	v_max3_f32 v202, v202, v94, v95
	v_max3_f32 v202, v202, v96, v97
	s_waitcnt lgkmcnt(6)
	v_mfma_f32_32x32x16_bf16 v[2:17], v[154:157], v[228:231], v[2:17]
	ds_read_b64_tr_b16 v[228:229], v242 offset:0x2200
	ds_read_b64_tr_b16 v[230:231], v242 offset:0x2a00
	ds_read_b64_tr_b16 v[238:239], v242 offset:0x3200
	ds_read_b64_tr_b16 v[240:241], v242 offset:0x3a00
	s_waitcnt lgkmcnt(8)
	v_mfma_f32_32x32x16_bf16 v[2:17], v[216:219], v[234:237], v[2:17]
	s_waitcnt lgkmcnt(6)
	v_mfma_f32_32x32x16_bf16 v[50:65], v[146:149], v[220:223], v[50:65]
	v_max3_f32 v202, v202, v66, v67
	v_max3_f32 v202, v202, v68, v69
	v_max3_f32 v202, v202, v70, v71
	v_max3_f32 v202, v202, v72, v73
	v_max3_f32 v202, v202, v74, v75
	v_max3_f32 v202, v202, v76, v77
	v_max3_f32 v202, v202, v78, v79
	s_waitcnt lgkmcnt(4)
	v_mfma_f32_32x32x16_bf16 v[50:65], v[150:153], v[224:227], v[50:65]
	v_max3_f32 v202, v202, v80, v81
	v_mov_b32_e32 v215, v202
	s_nop 1
	v_permlane32_swap_b32_e32 v202, v215
	v_max_f32_e32 v215, v215, v215
	v_max_f32_e32 v202, v202, v202
	v_max_f32_e32 v202, v202, v215
	v_max_f32_e32 v220, v165, v165
	v_sub_f32_e32 v215, v202, v165
	v_max_f32_e32 v202, v220, v202
	v_sub_f32_e32 v220, v165, v202
	v_mul_f32_e32 v220, 0x3dd53b94, v220
	s_waitcnt lgkmcnt(2)
	v_mfma_f32_32x32x16_bf16 v[50:65], v[154:157], v[228:231], v[50:65]
	v_exp_f32_e32 v220, v220
	v_cmp_ge_f32_e32 vcc, s77, v215
	s_cmp_eq_u64 vcc, exec
	s_cselect_b64 s[4:5], -1, 0
	v_cndmask_b32_e64 v215, v220, 1.0, s[4:5]
	ds_read_b64_tr_b16 v[220:221], v242 offset:0x400
	ds_read_b64_tr_b16 v[222:223], v242 offset:0xc00
	ds_read_b64_tr_b16 v[224:225], v242 offset:0x1400
	s_waitcnt lgkmcnt(3)
	v_mfma_f32_32x32x16_bf16 v[50:65], v[216:219], v[238:241], v[50:65]
	ds_read_b64_tr_b16 v[226:227], v242 offset:0x1c00
	ds_read_b64_tr_b16 v[228:229], v242 offset:0x2400
	ds_read_b64_tr_b16 v[230:231], v242 offset:0x2c00
	ds_read_b64_tr_b16 v[234:235], v242 offset:0x3400
	ds_read_b64_tr_b16 v[236:237], v242 offset:0x3c00
	s_waitcnt lgkmcnt(6)
	v_mfma_f32_32x32x16_bf16 v[34:49], v[146:149], v[220:223], v[34:49]
	ds_read_b64_tr_b16 v[220:221], v242 offset:0x600
	ds_read_b64_tr_b16 v[222:223], v242 offset:0xe00
	s_waitcnt lgkmcnt(6)
	v_mfma_f32_32x32x16_bf16 v[34:49], v[150:153], v[224:227], v[34:49]
	ds_read_b64_tr_b16 v[224:225], v242 offset:0x1600
	ds_read_b64_tr_b16 v[226:227], v242 offset:0x1e00
	s_waitcnt lgkmcnt(6)
	v_mfma_f32_32x32x16_bf16 v[34:49], v[154:157], v[228:231], v[34:49]
	ds_read_b64_tr_b16 v[228:229], v242 offset:0x2600
	ds_read_b64_tr_b16 v[230:231], v242 offset:0x2e00
	ds_read_b64_tr_b16 v[238:239], v242 offset:0x3600
	ds_read_b64_tr_b16 v[240:241], v242 offset:0x3e00
	s_waitcnt lgkmcnt(8)
	v_mfma_f32_32x32x16_bf16 v[34:49], v[216:219], v[234:237], v[34:49]
	s_waitcnt lgkmcnt(6)
	v_mfma_f32_32x32x16_bf16 v[18:33], v[146:149], v[220:223], v[18:33]
	v_cmp_gt_f32_e32 vcc, 1.0, v215
	s_waitcnt lgkmcnt(4)
	v_mfma_f32_32x32x16_bf16 v[18:33], v[150:153], v[224:227], v[18:33]
	s_waitcnt lgkmcnt(2)
	v_mfma_f32_32x32x16_bf16 v[18:33], v[154:157], v[228:231], v[18:33]
	s_waitcnt lgkmcnt(0)
	v_mfma_f32_32x32x16_bf16 v[18:33], v[216:219], v[238:241], v[18:33]
	s_cbranch_vccz .LBB0_553
	s_and_saveexec_b64 s[0:1], s[2:3]
	ds_write_b32 v170, v215 offset:128
	s_or_b64 exec, exec, s[0:1]
	s_waitcnt lgkmcnt(0)
	ds_read_b128 v[146:149], v158 offset:224
	ds_read_b128 v[150:153], v158 offset:192
	ds_read_b128 v[154:157], v158 offset:160
	ds_read_b128 v[216:219], v158 offset:128
	s_waitcnt lgkmcnt(0)
	v_pk_mul_f32 v[16:17], v[16:17], v[148:149]
	v_pk_mul_f32 v[12:13], v[12:13], v[152:153]
	v_pk_mul_f32 v[8:9], v[8:9], v[156:157]
	v_pk_mul_f32 v[4:5], v[4:5], v[218:219]
	v_pk_mul_f32 v[14:15], v[14:15], v[146:147]
	v_pk_mul_f32 v[10:11], v[10:11], v[150:151]
	v_pk_mul_f32 v[6:7], v[6:7], v[154:155]
	v_pk_mul_f32 v[2:3], v[2:3], v[216:217]
	v_pk_mul_f32 v[64:65], v[64:65], v[148:149]
	v_pk_mul_f32 v[60:61], v[60:61], v[152:153]
	v_pk_mul_f32 v[56:57], v[56:57], v[156:157]
	v_pk_mul_f32 v[52:53], v[52:53], v[218:219]
	v_pk_mul_f32 v[62:63], v[62:63], v[146:147]
	v_pk_mul_f32 v[58:59], v[58:59], v[150:151]
	v_pk_mul_f32 v[54:55], v[54:55], v[154:155]
	v_pk_mul_f32 v[50:51], v[50:51], v[216:217]
	v_pk_mul_f32 v[48:49], v[48:49], v[148:149]
	v_pk_mul_f32 v[44:45], v[44:45], v[152:153]
	v_pk_mul_f32 v[40:41], v[40:41], v[156:157]
	v_pk_mul_f32 v[36:37], v[36:37], v[218:219]
	v_pk_mul_f32 v[46:47], v[46:47], v[146:147]
	v_pk_mul_f32 v[42:43], v[42:43], v[150:151]
	v_pk_mul_f32 v[38:39], v[38:39], v[154:155]
	v_pk_mul_f32 v[34:35], v[34:35], v[216:217]
	v_pk_mul_f32 v[32:33], v[32:33], v[148:149]
	v_pk_mul_f32 v[28:29], v[28:29], v[152:153]
	v_pk_mul_f32 v[24:25], v[24:25], v[156:157]
	v_pk_mul_f32 v[20:21], v[20:21], v[218:219]
	v_pk_mul_f32 v[30:31], v[30:31], v[146:147]
	v_pk_mul_f32 v[26:27], v[26:27], v[150:151]
	v_pk_mul_f32 v[22:23], v[22:23], v[154:155]
	v_pk_mul_f32 v[18:19], v[18:19], v[216:217]
